# v65 + attention cross-half row max by v_permlane32_swap instead of ds_bpermute (instruction selection: DPP-class move instead of an LDS round trip)
# baseline (speedup 1.0000x reference)
; #define LAS __attribute__((address_space(3)))
; DI float shfl_xor_l(float v, int lane, int m) { return __int_as_float(__builtin_amdgcn_ds_bpermute((lane ^ m) << 2, __float_as_int(v))); }
; #define A_LOAD(kt) do { const size_t ko = (size_t)(kt) * 64; st0 = *(const u32x4*)(kn_src + ko * 2048); st1 = *(const u32x4*)(kn_src + (ko + 32) * 2048); \
;         st2 = *(const u32x4*)(kr_src + ko * 64); st3 = *(const u32x4*)(v_src + ko); st4 = *(const u32x4*)(v_src + ko + (size_t)64 * 8192); } while (0)
; DI void attn_unit(LAS unsigned char* lds, int wid, int b, int h, int qb) {
;     ...
;         if (kt + 1 < nkt) A_LOAD(kt + 1);
;         if (kt <= cq) {
;             LAS unsigned char* kb = lds + buf * ABUF; LAS unsigned char* vb = kb + KBYTES;
;             f32x16 s0, s1;
; #pragma unroll
;             for (int i = 0; i < 16; ++i) { s0[i] = 0.f; s1[i] = 0.f; }
;     ...
;             bf16x8 ka[3][2];
;             ka[0][0] = KLD(0, 0); ka[0][1] = KLD(0, 1); ka[1][0] = KLD(1, 0); ka[1][1] = KLD(1, 1);
; #pragma unroll
;             for (int ks = 0; ks < 12; ++ks) {
;                 if (ks + 2 < 12) { ka[(ks + 2) % 3][0] = KLD(ks + 2, 0); ka[(ks + 2) % 3][1] = KLD(ks + 2, 1); }
;                 s0 = __builtin_amdgcn_mfma_f32_32x32x16_bf16(ka[ks % 3][0], qf[ks], s0, 0, 0, 0); s1 = __builtin_amdgcn_mfma_f32_32x32x16_bf16(ka[ks % 3][1], qf[ks], s1, 0, 0, 0);
;                 __builtin_amdgcn_sched_barrier(0); }
;             u32x4 vf[2][4];
; #pragma unroll
;             for (int dt = 0; dt < 4; ++dt) VLD(vf[0][dt], 0, dt);
;             float mx = s0[0];
; #pragma unroll
;             for (int i = 1; i < 16; ++i) mx = fmaxf(mx, s0[i]);
; #pragma unroll
;             for (int i = 0; i < 16; ++i) mx = fmaxf(mx, s1[i]);
;             mx = fmaxf(mx, shfl_xor_l(mx, lane, 32));
;             const float mnew = fmaxf(mrow, mx), alpha = __builtin_amdgcn_exp2f(mrow - mnew); mrow = mnew;
;             float ls = 0.f;
; #pragma unroll
;             for (int i = 0; i < 16; ++i) { s0[i] = __builtin_amdgcn_exp2f(s0[i] - mnew); s1[i] = __builtin_amdgcn_exp2f(s1[i] - mnew); ls += s0[i] + s1[i]; }
;             lrow = lrow * alpha + ls;
;             if (__builtin_amdgcn_ballot_w64(alpha != 1.f) != 0ull) {
.LBB0_1079:
	v_lshl_add_u64 v[66:67], s[24:25], 0, v[194:195]
	v_add_co_u32_e32 v68, vcc, 0x11140000, v66
	s_and_b32 s65, s64, 1
	s_nop 0
	v_addc_co_u32_e32 v69, vcc, 0, v67, vcc
	v_add_co_u32_e32 v66, vcc, 0x11160000, v66
	s_cmp_gt_u32 s64, s62
	s_nop 0
	v_addc_co_u32_e32 v67, vcc, 0, v67, vcc
	global_load_dwordx4 v[146:149], v[68:69], off
	global_load_dwordx4 v[150:153], v[66:67], off
	v_lshl_add_u64 v[68:69], s[24:25], 0, v[190:191]
	v_add_co_u32_e32 v70, vcc, 0x13100000, v68
	v_lshl_add_u64 v[66:67], s[24:25], 0, v[192:193]
	s_nop 0
	v_addc_co_u32_e32 v71, vcc, 0, v69, vcc
	global_load_dwordx4 v[154:157], v[66:67], off
	global_load_dwordx4 v[158:161], v[70:71], off offset:128
	v_add_co_u32_e32 v66, vcc, 0x13200000, v68
	s_nop 1
	v_addc_co_u32_e32 v67, vcc, 0, v69, vcc
	global_load_dwordx4 v[162:165], v[66:67], off offset:128
	s_cbranch_scc1 .LBB0_1083
	s_mul_i32 s66, s65, 0xa800
	s_add_i32 s66, s66, 0
	v_add3_u32 v171, s66, v199, v202
	ds_read_b128 v[66:69], v171
	ds_read_b128 v[166:169], v171 offset:32
	ds_read_b128 v[82:85], v171 offset:12800
	ds_read_b128 v[172:175], v171 offset:64
	ds_read_b128 v[176:179], v171 offset:12832
	ds_read_b128 v[204:207], v171 offset:12864
	s_waitcnt lgkmcnt(3)
	v_mfma_f32_32x32x16_bf16 v[82:97], v[82:85], v[142:145], 0
	v_mfma_f32_32x32x16_bf16 v[66:81], v[66:69], v[142:145], 0
	v_mfma_f32_32x32x16_bf16 v[66:81], v[166:169], v[138:141], v[66:81]
	ds_read_b128 v[166:169], v171 offset:96
	ds_read_b128 v[208:211], v171 offset:12896
	s_waitcnt lgkmcnt(3)
	v_mfma_f32_32x32x16_bf16 v[82:97], v[176:179], v[138:141], v[82:97]
	v_mfma_f32_32x32x16_bf16 v[66:81], v[172:175], v[134:137], v[66:81]
	ds_read_b128 v[172:175], v171 offset:128
	ds_read_b128 v[176:179], v171 offset:12928
	s_waitcnt lgkmcnt(4)
	v_mfma_f32_32x32x16_bf16 v[82:97], v[204:207], v[134:137], v[82:97]
	s_waitcnt lgkmcnt(3)
	v_mfma_f32_32x32x16_bf16 v[66:81], v[166:169], v[130:133], v[66:81]
	ds_read_b128 v[166:169], v171 offset:160
	ds_read_b128 v[204:207], v171 offset:12960
	s_waitcnt lgkmcnt(4)
	v_mfma_f32_32x32x16_bf16 v[82:97], v[208:211], v[130:133], v[82:97]
	s_waitcnt lgkmcnt(3)
	v_mfma_f32_32x32x16_bf16 v[66:81], v[172:175], v[126:129], v[66:81]
	ds_read_b128 v[172:175], v171 offset:192
	ds_read_b128 v[208:211], v171 offset:12992
	s_waitcnt lgkmcnt(4)
	v_mfma_f32_32x32x16_bf16 v[82:97], v[176:179], v[126:129], v[82:97]
	s_waitcnt lgkmcnt(3)
	v_mfma_f32_32x32x16_bf16 v[66:81], v[166:169], v[122:125], v[66:81]
	ds_read_b128 v[166:169], v171 offset:224
	ds_read_b128 v[176:179], v171 offset:13024
	s_waitcnt lgkmcnt(4)
	v_mfma_f32_32x32x16_bf16 v[82:97], v[204:207], v[122:125], v[82:97]
	s_waitcnt lgkmcnt(3)
	v_mfma_f32_32x32x16_bf16 v[66:81], v[172:175], v[118:121], v[66:81]
	ds_read_b128 v[172:175], v171 offset:256
	ds_read_b128 v[204:207], v171 offset:13056
	s_waitcnt lgkmcnt(4)
	v_mfma_f32_32x32x16_bf16 v[82:97], v[208:211], v[118:121], v[82:97]
	s_waitcnt lgkmcnt(3)
	v_mfma_f32_32x32x16_bf16 v[66:81], v[166:169], v[114:117], v[66:81]
	ds_read_b128 v[166:169], v171 offset:288
	ds_read_b128 v[208:211], v171 offset:13088
	s_waitcnt lgkmcnt(4)
	v_mfma_f32_32x32x16_bf16 v[82:97], v[176:179], v[114:117], v[82:97]
	s_waitcnt lgkmcnt(3)
	v_mfma_f32_32x32x16_bf16 v[66:81], v[172:175], v[110:113], v[66:81]
	ds_read_b128 v[172:175], v171 offset:320
	ds_read_b128 v[176:179], v171 offset:13120
	s_waitcnt lgkmcnt(4)
	v_mfma_f32_32x32x16_bf16 v[82:97], v[204:207], v[110:113], v[82:97]
	s_waitcnt lgkmcnt(3)
	v_mfma_f32_32x32x16_bf16 v[66:81], v[166:169], v[106:109], v[66:81]
	ds_read_b128 v[166:169], v171 offset:352
	ds_read_b128 v[212:215], v171 offset:13152
	s_waitcnt lgkmcnt(4)
	v_mfma_f32_32x32x16_bf16 v[82:97], v[208:211], v[106:109], v[82:97]
	s_waitcnt lgkmcnt(3)
	v_mfma_f32_32x32x16_bf16 v[66:81], v[172:175], v[102:105], v[66:81]
	s_waitcnt lgkmcnt(2)
	v_mfma_f32_32x32x16_bf16 v[82:97], v[176:179], v[102:105], v[82:97]
	s_waitcnt lgkmcnt(1)
	v_mfma_f32_32x32x16_bf16 v[66:81], v[166:169], v[98:101], v[66:81]
	v_add_u32_e32 v171, s66, v184
	v_add_u32_e32 v171, v171, v189
	v_add_u32_e32 v204, 0x6000, v171
	v_add_u32_e32 v205, 0x7000, v171
	v_add_u32_e32 v206, 0x8000, v171
	v_add_u32_e32 v207, 0x9000, v171
	ds_read2_b64 v[166:169], v204 offset0:128 offset1:130
	s_nop 4
	v_max_f32_e32 v172, v67, v67
	v_max_f32_e32 v173, v66, v66
	v_max_f32_e32 v172, v173, v172
	s_waitcnt lgkmcnt(1)
	v_mfma_f32_32x32x16_bf16 v[82:97], v[212:215], v[98:101], v[82:97]
	v_max3_f32 v172, v172, v68, v69
	v_max3_f32 v172, v172, v70, v71
	v_max3_f32 v172, v172, v72, v73
	v_max3_f32 v172, v172, v74, v75
	v_max3_f32 v172, v172, v76, v77
	v_max3_f32 v172, v172, v78, v79
	v_max3_f32 v172, v172, v80, v81
	s_nop 4
	v_max3_f32 v172, v172, v82, v83
	v_max3_f32 v172, v172, v84, v85
	v_max3_f32 v172, v172, v86, v87
	v_max3_f32 v172, v172, v88, v89
	v_max3_f32 v172, v172, v90, v91
	v_max3_f32 v172, v172, v92, v93
	v_max3_f32 v172, v172, v94, v95
	v_max3_f32 v172, v172, v96, v97
	v_mov_b32_e32 v173, v172
	ds_read2_b64 v[178:181], v205 offset0:160 offset1:162
	ds_read2_b64 v[174:177], v206 offset0:192 offset1:194
	s_waitcnt lgkmcnt(2)
	s_nop 1
	v_permlane32_swap_b32 v173, v172
	v_max3_f32 v203, v170, v172, v173
	v_sub_f32_e32 v170, v170, v203
	v_exp_f32_e32 v196, v170
	ds_read2_b64 v[170:173], v207 offset0:224 offset1:226
	v_cmp_neq_f32_e32 vcc, 1.0, v196
	s_cbranch_vccz .LBB0_1082
; DI void attn_unit(LAS unsigned char* lds, int wid, int b, int h, int qb) {
;     ...
;             if (__builtin_amdgcn_ballot_w64(alpha != 1.f) != 0ull) {
; #pragma unroll
;                 for (int dt = 0; dt < 4; ++dt)
; #pragma unroll
;                     for (int i = 0; i < 16; ++i) o[dt][i] *= alpha;
;             }
	v_pk_mul_f32 v[64:65], v[64:65], v[196:197] op_sel_hi:[1,0]
	v_pk_mul_f32 v[62:63], v[62:63], v[196:197] op_sel_hi:[1,0]
	v_pk_mul_f32 v[60:61], v[60:61], v[196:197] op_sel_hi:[1,0]
	v_pk_mul_f32 v[58:59], v[58:59], v[196:197] op_sel_hi:[1,0]
	v_pk_mul_f32 v[56:57], v[56:57], v[196:197] op_sel_hi:[1,0]
	v_pk_mul_f32 v[54:55], v[54:55], v[196:197] op_sel_hi:[1,0]
	v_pk_mul_f32 v[52:53], v[52:53], v[196:197] op_sel_hi:[1,0]
	v_pk_mul_f32 v[50:51], v[50:51], v[196:197] op_sel_hi:[1,0]
	v_pk_mul_f32 v[48:49], v[48:49], v[196:197] op_sel_hi:[1,0]
	v_pk_mul_f32 v[46:47], v[46:47], v[196:197] op_sel_hi:[1,0]
	v_pk_mul_f32 v[44:45], v[44:45], v[196:197] op_sel_hi:[1,0]
	v_pk_mul_f32 v[42:43], v[42:43], v[196:197] op_sel_hi:[1,0]
	v_pk_mul_f32 v[40:41], v[40:41], v[196:197] op_sel_hi:[1,0]
	v_pk_mul_f32 v[38:39], v[38:39], v[196:197] op_sel_hi:[1,0]
	v_pk_mul_f32 v[36:37], v[36:37], v[196:197] op_sel_hi:[1,0]
	v_pk_mul_f32 v[34:35], v[34:35], v[196:197] op_sel_hi:[1,0]
	v_pk_mul_f32 v[32:33], v[32:33], v[196:197] op_sel_hi:[1,0]
	v_pk_mul_f32 v[30:31], v[30:31], v[196:197] op_sel_hi:[1,0]
	v_pk_mul_f32 v[28:29], v[28:29], v[196:197] op_sel_hi:[1,0]
	v_pk_mul_f32 v[26:27], v[26:27], v[196:197] op_sel_hi:[1,0]
	v_pk_mul_f32 v[24:25], v[24:25], v[196:197] op_sel_hi:[1,0]
	v_pk_mul_f32 v[22:23], v[22:23], v[196:197] op_sel_hi:[1,0]
	v_pk_mul_f32 v[20:21], v[20:21], v[196:197] op_sel_hi:[1,0]
	v_pk_mul_f32 v[18:19], v[18:19], v[196:197] op_sel_hi:[1,0]
	v_pk_mul_f32 v[16:17], v[16:17], v[196:197] op_sel_hi:[1,0]
	v_pk_mul_f32 v[14:15], v[14:15], v[196:197] op_sel_hi:[1,0]
	v_pk_mul_f32 v[12:13], v[12:13], v[196:197] op_sel_hi:[1,0]
	v_pk_mul_f32 v[10:11], v[10:11], v[196:197] op_sel_hi:[1,0]
	v_pk_mul_f32 v[8:9], v[8:9], v[196:197] op_sel_hi:[1,0]
	v_pk_mul_f32 v[6:7], v[6:7], v[196:197] op_sel_hi:[1,0]
	v_pk_mul_f32 v[4:5], v[4:5], v[196:197] op_sel_hi:[1,0]
	v_pk_mul_f32 v[2:3], v[2:3], v[196:197] op_sel_hi:[1,0]

; #define LAS __attribute__((address_space(3)))
; DI float shfl_xor_l(float v, int lane, int m) { return __int_as_float(__builtin_amdgcn_ds_bpermute((lane ^ m) << 2, __float_as_int(v))); }
; #define VLD(dst, j, dt) do { LAS unsigned char* va_ = vb + (32 * (dt) + n) * VROW + (16 * (j) + 4 * g) * 2; const u32x2 lo_ = *(const LAS u32x2*)(va_), hi_ = *(const LAS u32x2*)(va_ + 16); dst = (u32x4){lo_.x, lo_.y, hi_.x, hi_.y}; } while (0)
; DI void attn_unit(LAS unsigned char* lds, int wid, int b, int h, int qb) {
;     ...
;         if (kt <= cq) {
;             LAS unsigned char* kb = lds + buf * ABUF; LAS unsigned char* vb = kb + KBYTES;
;             f32x16 s0, s1;
; #pragma unroll
;             for (int i = 0; i < 16; ++i) { s0[i] = 0.f; s1[i] = 0.f; }
;     ...
;             bf16x8 ka[3][2];
;             ka[0][0] = KLD(0, 0); ka[0][1] = KLD(0, 1); ka[1][0] = KLD(1, 0); ka[1][1] = KLD(1, 1);
; #pragma unroll
;             for (int ks = 0; ks < 12; ++ks) {
;                 if (ks + 2 < 12) { ka[(ks + 2) % 3][0] = KLD(ks + 2, 0); ka[(ks + 2) % 3][1] = KLD(ks + 2, 1); }
;                 s0 = __builtin_amdgcn_mfma_f32_32x32x16_bf16(ka[ks % 3][0], qf[ks], s0, 0, 0, 0); s1 = __builtin_amdgcn_mfma_f32_32x32x16_bf16(ka[ks % 3][1], qf[ks], s1, 0, 0, 0);
;                 __builtin_amdgcn_sched_barrier(0); }
;             u32x4 vf[2][4];
; #pragma unroll
;             for (int dt = 0; dt < 4; ++dt) VLD(vf[0][dt], 0, dt);
;             float mx = s0[0];
; #pragma unroll
;             for (int i = 1; i < 16; ++i) mx = fmaxf(mx, s0[i]);
; #pragma unroll
;             for (int i = 0; i < 16; ++i) mx = fmaxf(mx, s1[i]);
;             mx = fmaxf(mx, shfl_xor_l(mx, lane, 32));
;             const float mnew = fmaxf(mrow, mx), alpha = __builtin_amdgcn_exp2f(mrow - mnew); mrow = mnew;
;             float ls = 0.f;
; #pragma unroll
;             for (int i = 0; i < 16; ++i) { s0[i] = __builtin_amdgcn_exp2f(s0[i] - mnew); s1[i] = __builtin_amdgcn_exp2f(s1[i] - mnew); ls += s0[i] + s1[i]; }
;             lrow = lrow * alpha + ls;
;             if (__builtin_amdgcn_ballot_w64(alpha != 1.f) != 0ull) {
; #pragma unroll
;                 for (int dt = 0; dt < 4; ++dt)
; #pragma unroll
;                     for (int i = 0; i < 16; ++i) o[dt][i] *= alpha;
;             }
.LBB0_1086:
	s_or_b32 s61, s61, 2
	s_cmp_ge_u32 s61, s62
	s_cbranch_scc1 .LBB0_1090
	s_bitcmp1_b32 s63, 0
	s_cselect_b32 s61, 0xa800, 0
	s_add_i32 s61, s61, 0
	v_add3_u32 v162, s61, v199, v202
	ds_read_b128 v[66:69], v162
	ds_read_b128 v[146:149], v162 offset:32
	ds_read_b128 v[82:85], v162 offset:12800
	ds_read_b128 v[150:153], v162 offset:64
	ds_read_b128 v[154:157], v162 offset:12832
	ds_read_b128 v[158:161], v162 offset:12864
	s_waitcnt lgkmcnt(3)
	v_mfma_f32_32x32x16_bf16 v[82:97], v[82:85], v[142:145], 0
	v_mfma_f32_32x32x16_bf16 v[66:81], v[66:69], v[142:145], 0
	v_mfma_f32_32x32x16_bf16 v[66:81], v[146:149], v[138:141], v[66:81]
	ds_read_b128 v[142:145], v162 offset:96
	ds_read_b128 v[146:149], v162 offset:12896
	s_waitcnt lgkmcnt(3)
	v_mfma_f32_32x32x16_bf16 v[82:97], v[154:157], v[138:141], v[82:97]
	v_mfma_f32_32x32x16_bf16 v[66:81], v[150:153], v[134:137], v[66:81]
	ds_read_b128 v[138:141], v162 offset:128
	ds_read_b128 v[150:153], v162 offset:12928
	s_waitcnt lgkmcnt(4)
	v_mfma_f32_32x32x16_bf16 v[82:97], v[158:161], v[134:137], v[82:97]
	s_waitcnt lgkmcnt(3)
	v_mfma_f32_32x32x16_bf16 v[66:81], v[142:145], v[130:133], v[66:81]
	ds_read_b128 v[134:137], v162 offset:160
	ds_read_b128 v[142:145], v162 offset:12960
	s_waitcnt lgkmcnt(4)
	v_mfma_f32_32x32x16_bf16 v[82:97], v[146:149], v[130:133], v[82:97]
	s_waitcnt lgkmcnt(3)
	v_mfma_f32_32x32x16_bf16 v[66:81], v[138:141], v[126:129], v[66:81]
	ds_read_b128 v[130:133], v162 offset:192
	ds_read_b128 v[138:141], v162 offset:12992
	s_waitcnt lgkmcnt(4)
	v_mfma_f32_32x32x16_bf16 v[82:97], v[150:153], v[126:129], v[82:97]
	s_waitcnt lgkmcnt(3)
	v_mfma_f32_32x32x16_bf16 v[66:81], v[134:137], v[122:125], v[66:81]
	ds_read_b128 v[126:129], v162 offset:224
	ds_read_b128 v[134:137], v162 offset:13024
	s_waitcnt lgkmcnt(4)
	v_mfma_f32_32x32x16_bf16 v[82:97], v[142:145], v[122:125], v[82:97]
	s_waitcnt lgkmcnt(3)
	v_mfma_f32_32x32x16_bf16 v[66:81], v[130:133], v[118:121], v[66:81]
	ds_read_b128 v[122:125], v162 offset:256
	ds_read_b128 v[130:133], v162 offset:13056
	s_waitcnt lgkmcnt(4)
	v_mfma_f32_32x32x16_bf16 v[82:97], v[138:141], v[118:121], v[82:97]
	s_waitcnt lgkmcnt(3)
	v_mfma_f32_32x32x16_bf16 v[66:81], v[126:129], v[114:117], v[66:81]
	ds_read_b128 v[118:121], v162 offset:288
	ds_read_b128 v[126:129], v162 offset:13088
	s_waitcnt lgkmcnt(4)
	v_mfma_f32_32x32x16_bf16 v[82:97], v[134:137], v[114:117], v[82:97]
	s_waitcnt lgkmcnt(3)
	v_mfma_f32_32x32x16_bf16 v[66:81], v[122:125], v[110:113], v[66:81]
	ds_read_b128 v[114:117], v162 offset:320
	ds_read_b128 v[122:125], v162 offset:13120
	s_waitcnt lgkmcnt(4)
	v_mfma_f32_32x32x16_bf16 v[82:97], v[130:133], v[110:113], v[82:97]
	s_waitcnt lgkmcnt(3)
	v_mfma_f32_32x32x16_bf16 v[66:81], v[118:121], v[106:109], v[66:81]
	ds_read_b128 v[110:113], v162 offset:352
	ds_read_b128 v[118:121], v162 offset:13152
	s_waitcnt lgkmcnt(4)
	v_mfma_f32_32x32x16_bf16 v[82:97], v[126:129], v[106:109], v[82:97]
	s_waitcnt lgkmcnt(3)
	v_mfma_f32_32x32x16_bf16 v[66:81], v[114:117], v[102:105], v[66:81]
	s_waitcnt lgkmcnt(2)
	v_mfma_f32_32x32x16_bf16 v[82:97], v[122:125], v[102:105], v[82:97]
	s_waitcnt lgkmcnt(1)
	v_mfma_f32_32x32x16_bf16 v[66:81], v[110:113], v[98:101], v[66:81]
	v_add_u32_e32 v102, s61, v184
	v_add_u32_e32 v122, v102, v189
	v_add_u32_e32 v115, 0x6000, v122
	v_add_u32_e32 v116, 0x7000, v122
	v_add_u32_e32 v117, 0x8000, v122
	ds_read2_b64 v[102:105], v115 offset0:128 offset1:130
	ds_read2_b64 v[110:113], v116 offset0:160 offset1:162
	s_nop 4
	v_max_f32_e32 v106, v67, v67
	v_max_f32_e32 v107, v66, v66
	v_max_f32_e32 v106, v107, v106
	s_waitcnt lgkmcnt(2)
	v_mfma_f32_32x32x16_bf16 v[82:97], v[118:121], v[98:101], v[82:97]
	v_max3_f32 v106, v106, v68, v69
	v_max3_f32 v106, v106, v70, v71
	v_max3_f32 v106, v106, v72, v73
	v_max3_f32 v106, v106, v74, v75
	v_max3_f32 v106, v106, v76, v77
	v_max3_f32 v106, v106, v78, v79
	v_max3_f32 v106, v106, v80, v81
	s_nop 4
	v_max3_f32 v98, v106, v82, v83
	v_max3_f32 v98, v98, v84, v85
	v_max3_f32 v98, v98, v86, v87
	v_max3_f32 v98, v98, v88, v89
	v_max3_f32 v98, v98, v90, v91
	v_max3_f32 v98, v98, v92, v93
	v_max3_f32 v98, v98, v94, v95
	v_max3_f32 v98, v98, v96, v97
	v_mov_b32_e32 v99, v98
	v_add_u32_e32 v118, 0x9000, v122
	ds_read2_b64 v[106:109], v117 offset0:192 offset1:194
	s_waitcnt lgkmcnt(1)
	s_nop 1
	v_permlane32_swap_b32 v99, v98
	v_max3_f32 v119, v203, v98, v99
	v_sub_f32_e32 v98, v203, v119
	v_exp_f32_e32 v114, v98
	ds_read2_b64 v[98:101], v118 offset0:224 offset1:226
	v_cmp_neq_f32_e32 vcc, 1.0, v114
	s_cbranch_vccz .LBB0_1089
	v_pk_mul_f32 v[64:65], v[64:65], v[114:115] op_sel_hi:[1,0]
	v_pk_mul_f32 v[62:63], v[62:63], v[114:115] op_sel_hi:[1,0]
	v_pk_mul_f32 v[60:61], v[60:61], v[114:115] op_sel_hi:[1,0]
	v_pk_mul_f32 v[58:59], v[58:59], v[114:115] op_sel_hi:[1,0]
	v_pk_mul_f32 v[56:57], v[56:57], v[114:115] op_sel_hi:[1,0]
	v_pk_mul_f32 v[54:55], v[54:55], v[114:115] op_sel_hi:[1,0]
	v_pk_mul_f32 v[52:53], v[52:53], v[114:115] op_sel_hi:[1,0]
	v_pk_mul_f32 v[50:51], v[50:51], v[114:115] op_sel_hi:[1,0]
	v_pk_mul_f32 v[48:49], v[48:49], v[114:115] op_sel_hi:[1,0]
	v_pk_mul_f32 v[46:47], v[46:47], v[114:115] op_sel_hi:[1,0]
	v_pk_mul_f32 v[44:45], v[44:45], v[114:115] op_sel_hi:[1,0]
	v_pk_mul_f32 v[42:43], v[42:43], v[114:115] op_sel_hi:[1,0]
	v_pk_mul_f32 v[40:41], v[40:41], v[114:115] op_sel_hi:[1,0]
	v_pk_mul_f32 v[38:39], v[38:39], v[114:115] op_sel_hi:[1,0]
	v_pk_mul_f32 v[36:37], v[36:37], v[114:115] op_sel_hi:[1,0]
	v_pk_mul_f32 v[34:35], v[34:35], v[114:115] op_sel_hi:[1,0]
	v_pk_mul_f32 v[32:33], v[32:33], v[114:115] op_sel_hi:[1,0]
	v_pk_mul_f32 v[30:31], v[30:31], v[114:115] op_sel_hi:[1,0]
	v_pk_mul_f32 v[28:29], v[28:29], v[114:115] op_sel_hi:[1,0]
	v_pk_mul_f32 v[26:27], v[26:27], v[114:115] op_sel_hi:[1,0]
	v_pk_mul_f32 v[24:25], v[24:25], v[114:115] op_sel_hi:[1,0]
	v_pk_mul_f32 v[22:23], v[22:23], v[114:115] op_sel_hi:[1,0]
	v_pk_mul_f32 v[20:21], v[20:21], v[114:115] op_sel_hi:[1,0]
	v_pk_mul_f32 v[18:19], v[18:19], v[114:115] op_sel_hi:[1,0]
	v_pk_mul_f32 v[16:17], v[16:17], v[114:115] op_sel_hi:[1,0]
	v_pk_mul_f32 v[14:15], v[14:15], v[114:115] op_sel_hi:[1,0]
	v_pk_mul_f32 v[12:13], v[12:13], v[114:115] op_sel_hi:[1,0]
	v_pk_mul_f32 v[10:11], v[10:11], v[114:115] op_sel_hi:[1,0]
	v_pk_mul_f32 v[8:9], v[8:9], v[114:115] op_sel_hi:[1,0]
	v_pk_mul_f32 v[6:7], v[6:7], v[114:115] op_sel_hi:[1,0]
	v_pk_mul_f32 v[4:5], v[4:5], v[114:115] op_sel_hi:[1,0]
	v_pk_mul_f32 v[2:3], v[2:3], v[114:115] op_sel_hi:[1,0]

; #define LAS __attribute__((address_space(3)))
; DI float shfl_xor_l(float v, int lane, int m) { return __int_as_float(__builtin_amdgcn_ds_bpermute((lane ^ m) << 2, __float_as_int(v))); }
; DI void attn_unit(LAS unsigned char* lds, int wid, int b, int h, int qb) {
;     ...
;     A_LOAD(0); A_WRITE(0); __syncthreads();
;     for (int kt = 0; kt < nkt; ++kt) {
;         const int buf = kt & 1;
;         if (kt + 1 < nkt) A_LOAD(kt + 1);
;         if (kt <= cq) {
;             LAS unsigned char* kb = lds + buf * ABUF; LAS unsigned char* vb = kb + KBYTES;
;             f32x16 s0, s1;
; #pragma unroll
;             for (int i = 0; i < 16; ++i) { s0[i] = 0.f; s1[i] = 0.f; }
;     ...
;             bf16x8 ka[3][2];
;             ka[0][0] = KLD(0, 0); ka[0][1] = KLD(0, 1); ka[1][0] = KLD(1, 0); ka[1][1] = KLD(1, 1);
; #pragma unroll
;             for (int ks = 0; ks < 12; ++ks) {
;                 if (ks + 2 < 12) { ka[(ks + 2) % 3][0] = KLD(ks + 2, 0); ka[(ks + 2) % 3][1] = KLD(ks + 2, 1); }
;                 s0 = __builtin_amdgcn_mfma_f32_32x32x16_bf16(ka[ks % 3][0], qf[ks], s0, 0, 0, 0); s1 = __builtin_amdgcn_mfma_f32_32x32x16_bf16(ka[ks % 3][1], qf[ks], s1, 0, 0, 0);
;                 __builtin_amdgcn_sched_barrier(0); }
;             u32x4 vf[2][4];
; #pragma unroll
;             for (int dt = 0; dt < 4; ++dt) VLD(vf[0][dt], 0, dt);
;             float mx = s0[0];
; #pragma unroll
;             for (int i = 1; i < 16; ++i) mx = fmaxf(mx, s0[i]);
; #pragma unroll
;             for (int i = 0; i < 16; ++i) mx = fmaxf(mx, s1[i]);
;             mx = fmaxf(mx, shfl_xor_l(mx, lane, 32));
;             const float mnew = fmaxf(mrow, mx), alpha = __builtin_amdgcn_exp2f(mrow - mnew); mrow = mnew;
;             float ls = 0.f;
; #pragma unroll
;             for (int i = 0; i < 16; ++i) { s0[i] = __builtin_amdgcn_exp2f(s0[i] - mnew); s1[i] = __builtin_amdgcn_exp2f(s1[i] - mnew); ls += s0[i] + s1[i]; }
;             lrow = lrow * alpha + ls;
;             if (__builtin_amdgcn_ballot_w64(alpha != 1.f) != 0ull) {
; #pragma unroll
;                 for (int dt = 0; dt < 4; ++dt)
; #pragma unroll
;                     for (int i = 0; i < 16; ++i) o[dt][i] *= alpha;
;             }
.LBB0_1091:
	v_lshl_add_u64 v[2:3], s[26:27], 0, v[198:199]
	v_add_co_u32_e32 v4, vcc, 0x11140000, v2
	v_lshl_add_u64 v[14:15], s[26:27], 0, v[194:195]
	s_nop 0
	v_addc_co_u32_e32 v5, vcc, 0, v3, vcc
	v_add_co_u32_e32 v6, vcc, 0x11160000, v2
	v_lshl_add_u64 v[10:11], s[26:27], 0, v[196:197]
	s_nop 0
	v_addc_co_u32_e32 v7, vcc, 0, v3, vcc
	v_add_co_u32_e32 v80, vcc, 0x13100000, v14
	global_load_dwordx4 v[2:5], v[4:5], off
	s_nop 0
	global_load_dwordx4 v[6:9], v[6:7], off
	v_addc_co_u32_e32 v81, vcc, 0, v15, vcc
	v_add_co_u32_e32 v14, vcc, 0x13200000, v14
	global_load_dwordx4 v[10:13], v[10:11], off
	s_nop 0
	global_load_dwordx4 v[160:163], v[80:81], off offset:128
	v_addc_co_u32_e32 v15, vcc, 0, v15, vcc
	global_load_dwordx4 v[164:167], v[14:15], off offset:128
	s_and_b32 s18, s57, 1
	s_cmp_gt_u32 s57, s25
	s_cbranch_scc1 .LBB0_1095
	s_mul_i32 s19, s18, 0xa800
	s_add_i32 s19, s19, 0
	v_add3_u32 v0, s19, v193, v204
	ds_read_b128 v[80:83], v0
	ds_read_b128 v[168:171], v0 offset:32
	ds_read_b128 v[96:99], v0 offset:12800
	ds_read_b128 v[174:177], v0 offset:64
	ds_read_b128 v[178:181], v0 offset:12832
	ds_read_b128 v[206:209], v0 offset:12864
	s_waitcnt vmcnt(6) lgkmcnt(3)
	v_mfma_f32_32x32x16_bf16 v[96:111], v[96:99], v[156:159], 0
	v_mfma_f32_32x32x16_bf16 v[80:95], v[80:83], v[156:159], 0
	v_mfma_f32_32x32x16_bf16 v[80:95], v[168:171], v[152:155], v[80:95]
	ds_read_b128 v[168:171], v0 offset:96
	ds_read_b128 v[210:213], v0 offset:12896
	s_waitcnt lgkmcnt(3)
	v_mfma_f32_32x32x16_bf16 v[96:111], v[178:181], v[152:155], v[96:111]
	v_mfma_f32_32x32x16_bf16 v[80:95], v[174:177], v[148:151], v[80:95]
	ds_read_b128 v[174:177], v0 offset:128
	ds_read_b128 v[178:181], v0 offset:12928
	s_waitcnt lgkmcnt(4)
	v_mfma_f32_32x32x16_bf16 v[96:111], v[206:209], v[148:151], v[96:111]
	s_waitcnt lgkmcnt(3)
	v_mfma_f32_32x32x16_bf16 v[80:95], v[168:171], v[144:147], v[80:95]
	ds_read_b128 v[168:171], v0 offset:160
	ds_read_b128 v[206:209], v0 offset:12960
	s_waitcnt lgkmcnt(4)
	v_mfma_f32_32x32x16_bf16 v[96:111], v[210:213], v[144:147], v[96:111]
	s_waitcnt lgkmcnt(3)
	v_mfma_f32_32x32x16_bf16 v[80:95], v[174:177], v[140:143], v[80:95]
	ds_read_b128 v[174:177], v0 offset:192
	ds_read_b128 v[210:213], v0 offset:12992
	s_waitcnt lgkmcnt(4)
	v_mfma_f32_32x32x16_bf16 v[96:111], v[178:181], v[140:143], v[96:111]
	s_waitcnt lgkmcnt(3)
	v_mfma_f32_32x32x16_bf16 v[80:95], v[168:171], v[136:139], v[80:95]
	ds_read_b128 v[168:171], v0 offset:224
	ds_read_b128 v[178:181], v0 offset:13024
	s_waitcnt lgkmcnt(4)
	v_mfma_f32_32x32x16_bf16 v[96:111], v[206:209], v[136:139], v[96:111]
	s_waitcnt lgkmcnt(3)
	v_mfma_f32_32x32x16_bf16 v[80:95], v[174:177], v[132:135], v[80:95]
	ds_read_b128 v[174:177], v0 offset:256
	ds_read_b128 v[206:209], v0 offset:13056
	s_waitcnt lgkmcnt(4)
	v_mfma_f32_32x32x16_bf16 v[96:111], v[210:213], v[132:135], v[96:111]
	s_waitcnt lgkmcnt(3)
	v_mfma_f32_32x32x16_bf16 v[80:95], v[168:171], v[128:131], v[80:95]
	ds_read_b128 v[168:171], v0 offset:288
	ds_read_b128 v[210:213], v0 offset:13088
	s_waitcnt lgkmcnt(4)
	v_mfma_f32_32x32x16_bf16 v[96:111], v[178:181], v[128:131], v[96:111]
	s_waitcnt lgkmcnt(3)
	v_mfma_f32_32x32x16_bf16 v[80:95], v[174:177], v[124:127], v[80:95]
	ds_read_b128 v[174:177], v0 offset:320
	ds_read_b128 v[178:181], v0 offset:13120
	s_waitcnt lgkmcnt(4)
	v_mfma_f32_32x32x16_bf16 v[96:111], v[206:209], v[124:127], v[96:111]
	s_waitcnt lgkmcnt(3)
	v_mfma_f32_32x32x16_bf16 v[80:95], v[168:171], v[120:123], v[80:95]
	ds_read_b128 v[168:171], v0 offset:352
	ds_read_b128 v[206:209], v0 offset:13152
	s_waitcnt lgkmcnt(4)
	v_mfma_f32_32x32x16_bf16 v[96:111], v[210:213], v[120:123], v[96:111]
	s_waitcnt lgkmcnt(3)
	v_mfma_f32_32x32x16_bf16 v[80:95], v[174:177], v[116:119], v[80:95]
	s_waitcnt lgkmcnt(2)
	v_mfma_f32_32x32x16_bf16 v[96:111], v[178:181], v[116:119], v[96:111]
	s_waitcnt vmcnt(5) lgkmcnt(1)
	v_mfma_f32_32x32x16_bf16 v[80:95], v[168:171], v[112:115], v[80:95]
	v_add_u32_e32 v0, s19, v188
	v_add_u32_e32 v173, v0, v191
	v_add_u32_e32 v15, 0x6000, v173
	v_add_u32_e32 v205, 0x7000, v173
	ds_read2_b64 v[168:171], v15 offset0:128 offset1:130
	ds_read2_b64 v[180:183], v205 offset0:160 offset1:162
	s_nop 5
	v_max_f32_e32 v0, v81, v81
	v_max_f32_e32 v14, v80, v80
	v_max_f32_e32 v0, v14, v0
	s_waitcnt lgkmcnt(2)
	v_mfma_f32_32x32x16_bf16 v[96:111], v[206:209], v[112:115], v[96:111]
	v_max3_f32 v0, v0, v82, v83
	v_max3_f32 v0, v0, v84, v85
	v_max3_f32 v0, v0, v86, v87
	v_max3_f32 v0, v0, v88, v89
	v_max3_f32 v0, v0, v90, v91
	v_max3_f32 v0, v0, v92, v93
	v_max3_f32 v0, v0, v94, v95
	s_nop 4
	v_max3_f32 v0, v0, v96, v97
	v_max3_f32 v0, v0, v98, v99
	v_max3_f32 v0, v0, v100, v101
	v_max3_f32 v0, v0, v102, v103
	v_max3_f32 v0, v0, v104, v105
	v_max3_f32 v0, v0, v106, v107
	v_max3_f32 v0, v0, v108, v109
	v_max3_f32 v0, v0, v110, v111
	v_mov_b32_e32 v14, v0
	v_add_u32_e32 v206, 0x8000, v173
	v_add_u32_e32 v207, 0x9000, v173
	ds_read2_b64 v[176:179], v206 offset0:192 offset1:194
	s_waitcnt lgkmcnt(1)
	s_nop 1
	v_permlane32_swap_b32 v14, v0
	v_max3_f32 v14, v172, v0, v14
	v_sub_f32_e32 v0, v172, v14
	v_exp_f32_e32 v0, v0
	ds_read2_b64 v[172:175], v207 offset0:224 offset1:226
	v_cmp_neq_f32_e32 vcc, 1.0, v0
	s_cbranch_vccz .LBB0_1094
	v_pk_mul_f32 v[78:79], v[78:79], v[0:1] op_sel_hi:[1,0]
	v_pk_mul_f32 v[76:77], v[76:77], v[0:1] op_sel_hi:[1,0]
	v_pk_mul_f32 v[74:75], v[74:75], v[0:1] op_sel_hi:[1,0]
	v_pk_mul_f32 v[72:73], v[72:73], v[0:1] op_sel_hi:[1,0]
	v_pk_mul_f32 v[70:71], v[70:71], v[0:1] op_sel_hi:[1,0]
	v_pk_mul_f32 v[68:69], v[68:69], v[0:1] op_sel_hi:[1,0]
	v_pk_mul_f32 v[66:67], v[66:67], v[0:1] op_sel_hi:[1,0]
	v_pk_mul_f32 v[64:65], v[64:65], v[0:1] op_sel_hi:[1,0]
	v_pk_mul_f32 v[62:63], v[62:63], v[0:1] op_sel_hi:[1,0]
	v_pk_mul_f32 v[60:61], v[60:61], v[0:1] op_sel_hi:[1,0]
	v_pk_mul_f32 v[58:59], v[58:59], v[0:1] op_sel_hi:[1,0]
	v_pk_mul_f32 v[56:57], v[56:57], v[0:1] op_sel_hi:[1,0]
	v_pk_mul_f32 v[54:55], v[54:55], v[0:1] op_sel_hi:[1,0]
	v_pk_mul_f32 v[52:53], v[52:53], v[0:1] op_sel_hi:[1,0]
	v_pk_mul_f32 v[50:51], v[50:51], v[0:1] op_sel_hi:[1,0]
	v_pk_mul_f32 v[48:49], v[48:49], v[0:1] op_sel_hi:[1,0]
	v_pk_mul_f32 v[46:47], v[46:47], v[0:1] op_sel_hi:[1,0]
	v_pk_mul_f32 v[44:45], v[44:45], v[0:1] op_sel_hi:[1,0]
	v_pk_mul_f32 v[42:43], v[42:43], v[0:1] op_sel_hi:[1,0]
	v_pk_mul_f32 v[40:41], v[40:41], v[0:1] op_sel_hi:[1,0]
	v_pk_mul_f32 v[38:39], v[38:39], v[0:1] op_sel_hi:[1,0]
	v_pk_mul_f32 v[36:37], v[36:37], v[0:1] op_sel_hi:[1,0]
	v_pk_mul_f32 v[34:35], v[34:35], v[0:1] op_sel_hi:[1,0]
	v_pk_mul_f32 v[32:33], v[32:33], v[0:1] op_sel_hi:[1,0]
	v_pk_mul_f32 v[30:31], v[30:31], v[0:1] op_sel_hi:[1,0]
	v_pk_mul_f32 v[28:29], v[28:29], v[0:1] op_sel_hi:[1,0]
	v_pk_mul_f32 v[26:27], v[26:27], v[0:1] op_sel_hi:[1,0]
	v_pk_mul_f32 v[24:25], v[24:25], v[0:1] op_sel_hi:[1,0]
	v_pk_mul_f32 v[22:23], v[22:23], v[0:1] op_sel_hi:[1,0]
	v_pk_mul_f32 v[20:21], v[20:21], v[0:1] op_sel_hi:[1,0]
	v_pk_mul_f32 v[18:19], v[18:19], v[0:1] op_sel_hi:[1,0]
	v_pk_mul_f32 v[16:17], v[16:17], v[0:1] op_sel_hi:[1,0]

; #define LAS __attribute__((address_space(3)))
; DI float shfl_xor_l(float v, int lane, int m) { return __int_as_float(__builtin_amdgcn_ds_bpermute((lane ^ m) << 2, __float_as_int(v))); }
; #define VLD(dst, j, dt) do { LAS unsigned char* va_ = vb + (32 * (dt) + n) * VROW + (16 * (j) + 4 * g) * 2; const u32x2 lo_ = *(const LAS u32x2*)(va_), hi_ = *(const LAS u32x2*)(va_ + 16); dst = (u32x4){lo_.x, lo_.y, hi_.x, hi_.y}; } while (0)
; DI void attn_unit(LAS unsigned char* lds, int wid, int b, int h, int qb) {
;     ...
;         if (kt <= cq) {
;             LAS unsigned char* kb = lds + buf * ABUF; LAS unsigned char* vb = kb + KBYTES;
;             f32x16 s0, s1;
; #pragma unroll
;             for (int i = 0; i < 16; ++i) { s0[i] = 0.f; s1[i] = 0.f; }
;     ...
;             bf16x8 ka[3][2];
;             ka[0][0] = KLD(0, 0); ka[0][1] = KLD(0, 1); ka[1][0] = KLD(1, 0); ka[1][1] = KLD(1, 1);
; #pragma unroll
;             for (int ks = 0; ks < 12; ++ks) {
;                 if (ks + 2 < 12) { ka[(ks + 2) % 3][0] = KLD(ks + 2, 0); ka[(ks + 2) % 3][1] = KLD(ks + 2, 1); }
;                 s0 = __builtin_amdgcn_mfma_f32_32x32x16_bf16(ka[ks % 3][0], qf[ks], s0, 0, 0, 0); s1 = __builtin_amdgcn_mfma_f32_32x32x16_bf16(ka[ks % 3][1], qf[ks], s1, 0, 0, 0);
;                 __builtin_amdgcn_sched_barrier(0); }
;             u32x4 vf[2][4];
; #pragma unroll
;             for (int dt = 0; dt < 4; ++dt) VLD(vf[0][dt], 0, dt);
;             float mx = s0[0];
; #pragma unroll
;             for (int i = 1; i < 16; ++i) mx = fmaxf(mx, s0[i]);
; #pragma unroll
;             for (int i = 0; i < 16; ++i) mx = fmaxf(mx, s1[i]);
;             mx = fmaxf(mx, shfl_xor_l(mx, lane, 32));
;             const float mnew = fmaxf(mrow, mx), alpha = __builtin_amdgcn_exp2f(mrow - mnew); mrow = mnew;
;             float ls = 0.f;
; #pragma unroll
;             for (int i = 0; i < 16; ++i) { s0[i] = __builtin_amdgcn_exp2f(s0[i] - mnew); s1[i] = __builtin_amdgcn_exp2f(s1[i] - mnew); ls += s0[i] + s1[i]; }
;             lrow = lrow * alpha + ls;
;             if (__builtin_amdgcn_ballot_w64(alpha != 1.f) != 0ull) {
; #pragma unroll
;                 for (int dt = 0; dt < 4; ++dt)
; #pragma unroll
;                     for (int i = 0; i < 16; ++i) o[dt][i] *= alpha;
;             }
.LBB0_1098:
	s_lshl_b32 s18, s56, 2
	s_or_b32 s18, s18, 2
	s_cmp_ge_u32 s18, s25
	s_cbranch_scc1 .LBB0_1077
	s_bitcmp1_b32 s4, 0
	s_cselect_b32 s4, 0xa800, 0
	s_add_i32 s4, s4, 0
	v_add3_u32 v0, s4, v193, v204
	ds_read_b128 v[2:5], v0
	ds_read_b128 v[6:9], v0 offset:32
	s_waitcnt lgkmcnt(1)
	v_mfma_f32_32x32x16_bf16 v[80:95], v[2:5], v[156:159], 0
	ds_read_b128 v[2:5], v0 offset:12800
	ds_read_b128 v[10:13], v0 offset:64
	ds_read_b128 v[160:163], v0 offset:12832
	ds_read_b128 v[164:167], v0 offset:12864
	s_waitcnt lgkmcnt(3)
	v_mfma_f32_32x32x16_bf16 v[96:111], v[2:5], v[156:159], 0
	v_mfma_f32_32x32x16_bf16 v[80:95], v[6:9], v[152:155], v[80:95]
	ds_read_b128 v[2:5], v0 offset:96
	ds_read_b128 v[6:9], v0 offset:12896
	s_waitcnt lgkmcnt(3)
	v_mfma_f32_32x32x16_bf16 v[96:111], v[160:163], v[152:155], v[96:111]
	v_mfma_f32_32x32x16_bf16 v[80:95], v[10:13], v[148:151], v[80:95]
	ds_read_b128 v[10:13], v0 offset:128
	ds_read_b128 v[152:155], v0 offset:12928
	s_waitcnt lgkmcnt(4)
	v_mfma_f32_32x32x16_bf16 v[96:111], v[164:167], v[148:151], v[96:111]
	s_waitcnt lgkmcnt(3)
	v_mfma_f32_32x32x16_bf16 v[80:95], v[2:5], v[144:147], v[80:95]
	ds_read_b128 v[2:5], v0 offset:160
	ds_read_b128 v[148:151], v0 offset:12960
	s_waitcnt lgkmcnt(4)
	v_mfma_f32_32x32x16_bf16 v[96:111], v[6:9], v[144:147], v[96:111]
	s_waitcnt lgkmcnt(3)
	v_mfma_f32_32x32x16_bf16 v[80:95], v[10:13], v[140:143], v[80:95]
	ds_read_b128 v[6:9], v0 offset:192
	ds_read_b128 v[10:13], v0 offset:12992
	s_waitcnt lgkmcnt(4)
	v_mfma_f32_32x32x16_bf16 v[96:111], v[152:155], v[140:143], v[96:111]
	s_waitcnt lgkmcnt(3)
	v_mfma_f32_32x32x16_bf16 v[80:95], v[2:5], v[136:139], v[80:95]
	ds_read_b128 v[2:5], v0 offset:224
	ds_read_b128 v[140:143], v0 offset:13024
	s_waitcnt lgkmcnt(4)
	v_mfma_f32_32x32x16_bf16 v[96:111], v[148:151], v[136:139], v[96:111]
	s_waitcnt lgkmcnt(3)
	v_mfma_f32_32x32x16_bf16 v[80:95], v[6:9], v[132:135], v[80:95]
	ds_read_b128 v[6:9], v0 offset:256
	ds_read_b128 v[136:139], v0 offset:13056
	s_waitcnt lgkmcnt(4)
	v_mfma_f32_32x32x16_bf16 v[96:111], v[10:13], v[132:135], v[96:111]
	s_waitcnt lgkmcnt(3)
	v_mfma_f32_32x32x16_bf16 v[80:95], v[2:5], v[128:131], v[80:95]
	ds_read_b128 v[2:5], v0 offset:288
	ds_read_b128 v[10:13], v0 offset:13088
	s_waitcnt lgkmcnt(4)
	v_mfma_f32_32x32x16_bf16 v[96:111], v[140:143], v[128:131], v[96:111]
	s_waitcnt lgkmcnt(3)
	v_mfma_f32_32x32x16_bf16 v[80:95], v[6:9], v[124:127], v[80:95]
	ds_read_b128 v[6:9], v0 offset:320
	ds_read_b128 v[128:131], v0 offset:13120
	s_waitcnt lgkmcnt(4)
	v_mfma_f32_32x32x16_bf16 v[96:111], v[136:139], v[124:127], v[96:111]
	s_waitcnt lgkmcnt(3)
	v_mfma_f32_32x32x16_bf16 v[80:95], v[2:5], v[120:123], v[80:95]
	ds_read_b128 v[2:5], v0 offset:352
	ds_read_b128 v[124:127], v0 offset:13152
	s_waitcnt lgkmcnt(4)
	v_mfma_f32_32x32x16_bf16 v[96:111], v[10:13], v[120:123], v[96:111]
	s_waitcnt lgkmcnt(3)
	v_mfma_f32_32x32x16_bf16 v[80:95], v[6:9], v[116:119], v[80:95]
	s_waitcnt lgkmcnt(2)
	v_mfma_f32_32x32x16_bf16 v[96:111], v[128:131], v[116:119], v[96:111]
	s_waitcnt lgkmcnt(1)
	v_mfma_f32_32x32x16_bf16 v[80:95], v[2:5], v[112:115], v[80:95]
	v_add_u32_e32 v0, s4, v188
	v_add_u32_e32 v6, v0, v191
	v_add_u32_e32 v15, 0x6000, v6
	v_add_u32_e32 v116, 0x7000, v6
	v_add_u32_e32 v117, 0x8000, v6
	ds_read2_b64 v[2:5], v15 offset0:128 offset1:130
	ds_read2_b64 v[10:13], v117 offset0:192 offset1:194
	s_nop 4
	v_max_f32_e32 v0, v81, v81
	v_max_f32_e32 v7, v80, v80
	v_max_f32_e32 v0, v7, v0
	s_waitcnt lgkmcnt(2)
	v_mfma_f32_32x32x16_bf16 v[96:111], v[124:127], v[112:115], v[96:111]
	v_max3_f32 v0, v0, v82, v83
	v_max3_f32 v0, v0, v84, v85
	v_max3_f32 v0, v0, v86, v87
	v_max3_f32 v0, v0, v88, v89
	v_max3_f32 v0, v0, v90, v91
	v_max3_f32 v0, v0, v92, v93
	v_max3_f32 v0, v0, v94, v95
	s_nop 4
	v_max3_f32 v0, v0, v96, v97
	v_max3_f32 v0, v0, v98, v99
	v_max3_f32 v0, v0, v100, v101
	v_max3_f32 v0, v0, v102, v103
	v_max3_f32 v0, v0, v104, v105
	v_max3_f32 v0, v0, v106, v107
	v_max3_f32 v0, v0, v108, v109
	v_max3_f32 v0, v0, v110, v111
	v_mov_b32_e32 v7, v0
	ds_read2_b64 v[112:115], v116 offset0:160 offset1:162
	s_waitcnt lgkmcnt(1)
	s_nop 1
	v_permlane32_swap_b32 v7, v0
	v_max3_f32 v118, v14, v0, v7
	v_sub_f32_e32 v0, v14, v118
	v_add_u32_e32 v14, 0x9000, v6
	v_exp_f32_e32 v0, v0
	ds_read2_b64 v[6:9], v14 offset0:224 offset1:226
	v_cmp_neq_f32_e32 vcc, 1.0, v0
	s_cbranch_vccz .LBB0_1076
	v_pk_mul_f32 v[78:79], v[78:79], v[0:1] op_sel_hi:[1,0]
	v_pk_mul_f32 v[76:77], v[76:77], v[0:1] op_sel_hi:[1,0]
	v_pk_mul_f32 v[74:75], v[74:75], v[0:1] op_sel_hi:[1,0]
	v_pk_mul_f32 v[72:73], v[72:73], v[0:1] op_sel_hi:[1,0]
	v_pk_mul_f32 v[70:71], v[70:71], v[0:1] op_sel_hi:[1,0]
	v_pk_mul_f32 v[68:69], v[68:69], v[0:1] op_sel_hi:[1,0]
	v_pk_mul_f32 v[66:67], v[66:67], v[0:1] op_sel_hi:[1,0]
	v_pk_mul_f32 v[64:65], v[64:65], v[0:1] op_sel_hi:[1,0]
	v_pk_mul_f32 v[62:63], v[62:63], v[0:1] op_sel_hi:[1,0]
	v_pk_mul_f32 v[60:61], v[60:61], v[0:1] op_sel_hi:[1,0]
	v_pk_mul_f32 v[58:59], v[58:59], v[0:1] op_sel_hi:[1,0]
	v_pk_mul_f32 v[56:57], v[56:57], v[0:1] op_sel_hi:[1,0]
	v_pk_mul_f32 v[54:55], v[54:55], v[0:1] op_sel_hi:[1,0]
	v_pk_mul_f32 v[52:53], v[52:53], v[0:1] op_sel_hi:[1,0]
	v_pk_mul_f32 v[50:51], v[50:51], v[0:1] op_sel_hi:[1,0]
	v_pk_mul_f32 v[48:49], v[48:49], v[0:1] op_sel_hi:[1,0]
	v_pk_mul_f32 v[46:47], v[46:47], v[0:1] op_sel_hi:[1,0]
	v_pk_mul_f32 v[44:45], v[44:45], v[0:1] op_sel_hi:[1,0]
	v_pk_mul_f32 v[42:43], v[42:43], v[0:1] op_sel_hi:[1,0]
	v_pk_mul_f32 v[40:41], v[40:41], v[0:1] op_sel_hi:[1,0]
	v_pk_mul_f32 v[38:39], v[38:39], v[0:1] op_sel_hi:[1,0]
	v_pk_mul_f32 v[36:37], v[36:37], v[0:1] op_sel_hi:[1,0]
	v_pk_mul_f32 v[34:35], v[34:35], v[0:1] op_sel_hi:[1,0]
	v_pk_mul_f32 v[32:33], v[32:33], v[0:1] op_sel_hi:[1,0]
	v_pk_mul_f32 v[30:31], v[30:31], v[0:1] op_sel_hi:[1,0]
	v_pk_mul_f32 v[28:29], v[28:29], v[0:1] op_sel_hi:[1,0]
	v_pk_mul_f32 v[26:27], v[26:27], v[0:1] op_sel_hi:[1,0]
	v_pk_mul_f32 v[24:25], v[24:25], v[0:1] op_sel_hi:[1,0]
	v_pk_mul_f32 v[22:23], v[22:23], v[0:1] op_sel_hi:[1,0]
	v_pk_mul_f32 v[20:21], v[20:21], v[0:1] op_sel_hi:[1,0]
	v_pk_mul_f32 v[18:19], v[18:19], v[0:1] op_sel_hi:[1,0]
	v_pk_mul_f32 v[16:17], v[16:17], v[0:1] op_sel_hi:[1,0]
	s_branch .LBB0_1076
